# mLSTM phase: static priority raise only for waves 6-7 (the causal-work pole) instead of waves 4-7
# speedup vs baseline: 1.0062x; 1.0025x over previous
; #define LAS __attribute__((address_space(3)))
; __device__ __forceinline__ void p2_mlstm(const Params& p, LAS unsigned char* lds) {
;     const int tid = threadIdx.x, wid = __builtin_amdgcn_readfirstlane(tid >> 6), lane = tid & 63, r = lane & 15, q = lane >> 4;
;     unsigned char* ws = p.ws;
;     const bf16_t* R1 = (const bf16_t*)(ws + WS_R1); const bf16_t* QK = (const bf16_t*)(ws + WS_R2);
;     const float* GATES = (const float*)(ws + WS_GATES);
;     float* SSQ = (float*)(ws + WS_SSQ);
;     bf16_t* HM = (bf16_t*)((unsigned char*)p.out + OUT_HM);
;     LAS unsigned char* KB = lds + ML_KB; LAS unsigned char* VT = lds + ML_VT; LAS unsigned char* CT = lds + ML_CT; LAS unsigned char* WVT = lds + ML_WVT;
;     LAS unsigned char* NV = lds + 149760;
;     LAS unsigned char* WV = lds + 150272;
;     LAS float* PU = (LAS float*)(lds + ML_G); LAS float* PCM = PU + 2048; LAS float* PB = PU + 4096; LAS float* PBT = PU + 6144; LAS float* PCT = PBT + 16; LAS float* MPREV = PBT + 32; LAS float* MM127 = PBT + 48;
;     for (int it = blockIdx.x; it < 256; it += gridDim.x) {
;     ...
;                     const int nb = 4 * ((wid >> 1) + 1);
.LBB0_233:
	s_cmp_lt_i32 s90, 4
	s_cselect_b64 s[0:1], -1, 0
	s_add_u32 s4, s74, 0x2000000
	s_addc_u32 s5, s75, 0
	v_writelane_b32 v254, s4, 23
	s_and_b64 s[0:1], s[0:1], s[2:3]
	s_nop 0
	v_writelane_b32 v254, s5, 24
	v_writelane_b32 v254, s0, 25
	s_andn2_b64 vcc, exec, s[0:1]
	s_nop 0
	v_writelane_b32 v254, s1, 26
	s_cbranch_vccnz .LBB0_359
	s_cmpk_gt_i32 s84, 0xff
	v_readfirstlane_b32 s0, v212
	s_cbranch_scc1 .LBB0_359
	s_cmp_ge_u32 s0, 0x180
	s_cbranch_scc0 .Lprio3_done
	s_setprio 1
